# plus hand-written modulate_rows (LDS modulation table, two-bank group prefetch)
# baseline (speedup 1.0000x reference)
; __device__ __forceinline__ unsigned pk2(float lo, float hi) { return f2bf(lo) | (f2bf(hi) << 16); }
; __device__ __forceinline__ void modulate_rows(const Args& a, const float* mod0, bf16* U, int gw, int ngw, int lane) {
;     for (int m = gw; m < MT; m += ngw) {
;         const bool lat = m < ML; const int bb = lat ? (m >> 12) : 8;
;         const float* xr = lat ? a.x + (size_t)m * DM : a.ctx + (size_t)(m - ML) * DM;
;         const float* mp = mod0 + (size_t)bb * 6144;
; #pragma unroll
;         for (int j = 0; j < 4; ++j) { const int col = 4 * (lane + 64 * j); const f32x4 v = *(const f32x4*)(xr + col), sh = *(const f32x4*)(mp + col), sc = *(const f32x4*)(mp + 1024 + col);
;             const f32x4 o = v * (sc + 1.0f) + sh; v2u w; w.x = pk2(o[0], o[1]); w.y = pk2(o[2], o[3]); *(v2u*)(U + (size_t)m * DM + col) = w; }
;     }
; }
.Lmodx_entry:
	v_mbcnt_lo_u32_b32 v2, -1, 0
	v_mbcnt_hi_u32_b32 v2, -1, v2
	v_readfirstlane_b32 s0, v212
	v_readlane_b32 s4, v252, 6
	v_readlane_b32 s5, v252, 7
	v_lshlrev_b32_e32 v3, 4, v2
	v_lshlrev_b32_e32 v4, 3, v2
	s_nop 3
	s_lshr_b32 s0, s0, 6
	s_add_i32 s7, s0, s54
	s_mul_i32 s1, s0, 0x6000
	s_add_u32 s8, s4, s1
	s_addc_u32 s9, s5, 0
	s_lshl_b32 s10, s0, 13
	s_mov_b32 m0, s10
	s_nop 0
	global_load_lds_dwordx4 v3, s[8:9] offset:0
	global_load_lds_dwordx4 v3, s[8:9] offset:1024
	global_load_lds_dwordx4 v3, s[8:9] offset:2048
	global_load_lds_dwordx4 v3, s[8:9] offset:3072
	s_add_u32 s8, s8, 0x1000
	s_addc_u32 s9, s9, 0
	s_add_i32 s10, s10, 0x1000
	s_mov_b32 m0, s10
	s_nop 0
	global_load_lds_dwordx4 v3, s[8:9] offset:0
	global_load_lds_dwordx4 v3, s[8:9] offset:1024
	global_load_lds_dwordx4 v3, s[8:9] offset:2048
	global_load_lds_dwordx4 v3, s[8:9] offset:3072
	s_lshl_b32 s1, s0, 10
	s_add_u32 s8, s4, 0x30000
	s_addc_u32 s9, s5, 0
	s_add_u32 s8, s8, s1
	s_addc_u32 s9, s9, 0
	s_add_i32 s10, s1, 0x10000
	s_mov_b32 m0, s10
	s_nop 0
	global_load_lds_dwordx4 v3, s[8:9]
	s_mul_i32 s0, s38, 0
	s_add_i32 s0, s0, s7
	s_min_i32 s0, s0, 0x87ff
	s_cmp_lt_i32 s0, 0x8000
	s_cselect_b32 s2, s68, s72
	s_cselect_b32 s3, s69, s73
	s_cselect_b32 s1, 0, 0x8000
	s_sub_i32 s0, s0, s1
	s_lshl_b32 s0, s0, 12
	s_add_u32 s2, s2, s0
	s_addc_u32 s3, s3, 0
	global_load_dwordx4 v[16:19], v3, s[2:3]
	global_load_dwordx4 v[20:23], v3, s[2:3] offset:1024
	global_load_dwordx4 v[24:27], v3, s[2:3] offset:2048
	global_load_dwordx4 v[28:31], v3, s[2:3] offset:3072
	s_mul_i32 s0, s38, 1
	s_add_i32 s0, s0, s7
	s_min_i32 s0, s0, 0x87ff
	s_cmp_lt_i32 s0, 0x8000
	s_cselect_b32 s2, s68, s72
	s_cselect_b32 s3, s69, s73
	s_cselect_b32 s1, 0, 0x8000
	s_sub_i32 s0, s0, s1
	s_lshl_b32 s0, s0, 12
	s_add_u32 s2, s2, s0
	s_addc_u32 s3, s3, 0
	global_load_dwordx4 v[32:35], v3, s[2:3]
	global_load_dwordx4 v[36:39], v3, s[2:3] offset:1024
	global_load_dwordx4 v[40:43], v3, s[2:3] offset:2048
	global_load_dwordx4 v[44:47], v3, s[2:3] offset:3072
	s_mul_i32 s0, s38, 2
	s_add_i32 s0, s0, s7
	s_min_i32 s0, s0, 0x87ff
	s_cmp_lt_i32 s0, 0x8000
	s_cselect_b32 s2, s68, s72
	s_cselect_b32 s3, s69, s73
	s_cselect_b32 s1, 0, 0x8000
	s_sub_i32 s0, s0, s1
	s_lshl_b32 s0, s0, 12
	s_add_u32 s2, s2, s0
	s_addc_u32 s3, s3, 0
	global_load_dwordx4 v[48:51], v3, s[2:3]
	global_load_dwordx4 v[52:55], v3, s[2:3] offset:1024
	global_load_dwordx4 v[56:59], v3, s[2:3] offset:2048
	global_load_dwordx4 v[60:63], v3, s[2:3] offset:3072
	s_mul_i32 s0, s38, 3
	s_add_i32 s0, s0, s7
	s_min_i32 s0, s0, 0x87ff
	s_cmp_lt_i32 s0, 0x8000
	s_cselect_b32 s2, s68, s72
	s_cselect_b32 s3, s69, s73
	s_cselect_b32 s1, 0, 0x8000
	s_sub_i32 s0, s0, s1
	s_lshl_b32 s0, s0, 12
	s_add_u32 s2, s2, s0
	s_addc_u32 s3, s3, 0
	global_load_dwordx4 v[64:67], v3, s[2:3]
	global_load_dwordx4 v[68:71], v3, s[2:3] offset:1024
	global_load_dwordx4 v[72:75], v3, s[2:3] offset:2048
	global_load_dwordx4 v[76:79], v3, s[2:3] offset:3072
	s_waitcnt vmcnt(0)
	s_barrier
	s_cmp_lt_i32 s7, 0x8800
	s_cbranch_scc0 .Lmodx_done
.Lmodx_loop:
	s_lshl_b32 s0, s38, 2
	s_add_i32 s11, s7, s0
	s_mul_i32 s0, s38, 0
	s_add_i32 s0, s0, s11
	s_min_i32 s0, s0, 0x87ff
	s_cmp_lt_i32 s0, 0x8000
	s_cselect_b32 s2, s68, s72
	s_cselect_b32 s3, s69, s73
	s_cselect_b32 s1, 0, 0x8000
	s_sub_i32 s0, s0, s1
	s_lshl_b32 s0, s0, 12
	s_add_u32 s2, s2, s0
	s_addc_u32 s3, s3, 0
	global_load_dwordx4 v[96:99], v3, s[2:3]
	global_load_dwordx4 v[100:103], v3, s[2:3] offset:1024
	global_load_dwordx4 v[104:107], v3, s[2:3] offset:2048
	global_load_dwordx4 v[108:111], v3, s[2:3] offset:3072
	s_mul_i32 s0, s38, 1
	s_add_i32 s0, s0, s11
	s_min_i32 s0, s0, 0x87ff
	s_cmp_lt_i32 s0, 0x8000
	s_cselect_b32 s2, s68, s72
	s_cselect_b32 s3, s69, s73
	s_cselect_b32 s1, 0, 0x8000
	s_sub_i32 s0, s0, s1
	s_lshl_b32 s0, s0, 12
	s_add_u32 s2, s2, s0
	s_addc_u32 s3, s3, 0
	global_load_dwordx4 v[112:115], v3, s[2:3]
	global_load_dwordx4 v[116:119], v3, s[2:3] offset:1024
	global_load_dwordx4 v[120:123], v3, s[2:3] offset:2048
	global_load_dwordx4 v[124:127], v3, s[2:3] offset:3072
	s_mul_i32 s0, s38, 2
	s_add_i32 s0, s0, s11
	s_min_i32 s0, s0, 0x87ff
	s_cmp_lt_i32 s0, 0x8000
	s_cselect_b32 s2, s68, s72
	s_cselect_b32 s3, s69, s73
	s_cselect_b32 s1, 0, 0x8000
	s_sub_i32 s0, s0, s1
	s_lshl_b32 s0, s0, 12
	s_add_u32 s2, s2, s0
	s_addc_u32 s3, s3, 0
	global_load_dwordx4 v[128:131], v3, s[2:3]
	global_load_dwordx4 v[132:135], v3, s[2:3] offset:1024
	global_load_dwordx4 v[136:139], v3, s[2:3] offset:2048
	global_load_dwordx4 v[140:143], v3, s[2:3] offset:3072
	s_mul_i32 s0, s38, 3
	s_add_i32 s0, s0, s11
	s_min_i32 s0, s0, 0x87ff
	s_cmp_lt_i32 s0, 0x8000
	s_cselect_b32 s2, s68, s72
	s_cselect_b32 s3, s69, s73
	s_cselect_b32 s1, 0, 0x8000
	s_sub_i32 s0, s0, s1
	s_lshl_b32 s0, s0, 12
	s_add_u32 s2, s2, s0
	s_addc_u32 s3, s3, 0
	global_load_dwordx4 v[144:147], v3, s[2:3]
	global_load_dwordx4 v[148:151], v3, s[2:3] offset:1024
	global_load_dwordx4 v[152:155], v3, s[2:3] offset:2048
	global_load_dwordx4 v[156:159], v3, s[2:3] offset:3072
	s_waitcnt vmcnt(32)
	s_mul_i32 s0, s38, 0
	s_add_i32 s0, s0, s7
	s_cmp_lt_i32 s0, 0x8800
	s_cbranch_scc0 .Lmodx_skip_b0_0
; __device__ __forceinline__ unsigned pk2(float lo, float hi) { return f2bf(lo) | (f2bf(hi) << 16); }
; __device__ __forceinline__ void modulate_rows(const Args& a, const float* mod0, bf16* U, int gw, int ngw, int lane) {
;     ...
;         const bool lat = m < ML; const int bb = lat ? (m >> 12) : 8;
;         const float* xr = lat ? a.x + (size_t)m * DM : a.ctx + (size_t)(m - ML) * DM;
;         const float* mp = mod0 + (size_t)bb * 6144;
; #pragma unroll
;         for (int j = 0; j < 4; ++j) { const int col = 4 * (lane + 64 * j); const f32x4 v = *(const f32x4*)(xr + col), sh = *(const f32x4*)(mp + col), sc = *(const f32x4*)(mp + 1024 + col);
;             const f32x4 o = v * (sc + 1.0f) + sh; v2u w; w.x = pk2(o[0], o[1]); w.y = pk2(o[2], o[3]); *(v2u*)(U + (size_t)m * DM + col) = w; }
	s_min_i32 s1, s0, 0x8000
	s_lshr_b32 s1, s1, 12
	s_lshl_b32 s1, s1, 13
	v_add_u32_e32 v5, s1, v3
	s_lshl_b32 s0, s0, 11
	s_add_u32 s2, s64, s0
	s_addc_u32 s3, s65, 0
	ds_read_b128 v[160:163], v5 offset:0
	ds_read_b128 v[164:167], v5 offset:1024
	ds_read_b128 v[168:171], v5 offset:2048
	ds_read_b128 v[172:175], v5 offset:3072
	ds_read_b128 v[176:179], v5 offset:4096
	ds_read_b128 v[180:183], v5 offset:5120
	ds_read_b128 v[184:187], v5 offset:6144
	ds_read_b128 v[188:191], v5 offset:7168
	s_waitcnt lgkmcnt(0)
	v_add_f32_e32 v176, 1.0, v176
	v_add_f32_e32 v177, 1.0, v177
	v_add_f32_e32 v178, 1.0, v178
	v_add_f32_e32 v179, 1.0, v179
	v_fma_f32 v16, v16, v176, v160
	v_fma_f32 v17, v17, v177, v161
	v_fma_f32 v18, v18, v178, v162
	v_fma_f32 v19, v19, v179, v163
	v_cvt_pk_bf16_f32 v192, v16, v17
	v_cvt_pk_bf16_f32 v193, v18, v19
	global_store_dwordx2 v4, v[192:193], s[2:3]
	s_nop 0
	v_add_f32_e32 v180, 1.0, v180
	v_add_f32_e32 v181, 1.0, v181
	v_add_f32_e32 v182, 1.0, v182
	v_add_f32_e32 v183, 1.0, v183
	v_fma_f32 v20, v20, v180, v164
	v_fma_f32 v21, v21, v181, v165
	v_fma_f32 v22, v22, v182, v166
	v_fma_f32 v23, v23, v183, v167
	v_cvt_pk_bf16_f32 v194, v20, v21
	v_cvt_pk_bf16_f32 v195, v22, v23
	global_store_dwordx2 v4, v[194:195], s[2:3] offset:512
	s_nop 0
	v_add_f32_e32 v184, 1.0, v184
	v_add_f32_e32 v185, 1.0, v185
	v_add_f32_e32 v186, 1.0, v186
	v_add_f32_e32 v187, 1.0, v187
	v_fma_f32 v24, v24, v184, v168
	v_fma_f32 v25, v25, v185, v169
	v_fma_f32 v26, v26, v186, v170
	v_fma_f32 v27, v27, v187, v171
	v_cvt_pk_bf16_f32 v196, v24, v25
	v_cvt_pk_bf16_f32 v197, v26, v27
	global_store_dwordx2 v4, v[196:197], s[2:3] offset:1024
	s_nop 0
	v_add_f32_e32 v188, 1.0, v188
	v_add_f32_e32 v189, 1.0, v189
	v_add_f32_e32 v190, 1.0, v190
	v_add_f32_e32 v191, 1.0, v191
	v_fma_f32 v28, v28, v188, v172
	v_fma_f32 v29, v29, v189, v173
	v_fma_f32 v30, v30, v190, v174
	v_fma_f32 v31, v31, v191, v175
	v_cvt_pk_bf16_f32 v198, v28, v29
	v_cvt_pk_bf16_f32 v199, v30, v31
	global_store_dwordx2 v4, v[198:199], s[2:3] offset:1536
.Lmodx_skip_b0_0:
	s_mul_i32 s0, s38, 1
	s_add_i32 s0, s0, s7
	s_cmp_lt_i32 s0, 0x8800
	s_cbranch_scc0 .Lmodx_skip_b0_1
	s_min_i32 s1, s0, 0x8000
	s_lshr_b32 s1, s1, 12
	s_lshl_b32 s1, s1, 13
	v_add_u32_e32 v5, s1, v3
	s_lshl_b32 s0, s0, 11
	s_add_u32 s2, s64, s0
	s_addc_u32 s3, s65, 0
	ds_read_b128 v[160:163], v5 offset:0
	ds_read_b128 v[164:167], v5 offset:1024
	ds_read_b128 v[168:171], v5 offset:2048
	ds_read_b128 v[172:175], v5 offset:3072
	ds_read_b128 v[176:179], v5 offset:4096
	ds_read_b128 v[180:183], v5 offset:5120
	ds_read_b128 v[184:187], v5 offset:6144
	ds_read_b128 v[188:191], v5 offset:7168
	s_waitcnt lgkmcnt(0)
	v_add_f32_e32 v176, 1.0, v176
	v_add_f32_e32 v177, 1.0, v177
	v_add_f32_e32 v178, 1.0, v178
	v_add_f32_e32 v179, 1.0, v179
	v_fma_f32 v32, v32, v176, v160
	v_fma_f32 v33, v33, v177, v161
	v_fma_f32 v34, v34, v178, v162
	v_fma_f32 v35, v35, v179, v163
	v_cvt_pk_bf16_f32 v192, v32, v33
	v_cvt_pk_bf16_f32 v193, v34, v35
	global_store_dwordx2 v4, v[192:193], s[2:3]
	s_nop 0
	v_add_f32_e32 v180, 1.0, v180
	v_add_f32_e32 v181, 1.0, v181
	v_add_f32_e32 v182, 1.0, v182
	v_add_f32_e32 v183, 1.0, v183
	v_fma_f32 v36, v36, v180, v164
	v_fma_f32 v37, v37, v181, v165
	v_fma_f32 v38, v38, v182, v166
	v_fma_f32 v39, v39, v183, v167
	v_cvt_pk_bf16_f32 v194, v36, v37
	v_cvt_pk_bf16_f32 v195, v38, v39
	global_store_dwordx2 v4, v[194:195], s[2:3] offset:512
	s_nop 0
	v_add_f32_e32 v184, 1.0, v184
	v_add_f32_e32 v185, 1.0, v185
	v_add_f32_e32 v186, 1.0, v186
	v_add_f32_e32 v187, 1.0, v187
	v_fma_f32 v40, v40, v184, v168
	v_fma_f32 v41, v41, v185, v169
	v_fma_f32 v42, v42, v186, v170
	v_fma_f32 v43, v43, v187, v171
	v_cvt_pk_bf16_f32 v196, v40, v41
	v_cvt_pk_bf16_f32 v197, v42, v43
	global_store_dwordx2 v4, v[196:197], s[2:3] offset:1024
	s_nop 0
	v_add_f32_e32 v188, 1.0, v188
	v_add_f32_e32 v189, 1.0, v189
	v_add_f32_e32 v190, 1.0, v190
	v_add_f32_e32 v191, 1.0, v191
	v_fma_f32 v44, v44, v188, v172
	v_fma_f32 v45, v45, v189, v173
	v_fma_f32 v46, v46, v190, v174
	v_fma_f32 v47, v47, v191, v175
	v_cvt_pk_bf16_f32 v198, v44, v45
	v_cvt_pk_bf16_f32 v199, v46, v47
	global_store_dwordx2 v4, v[198:199], s[2:3] offset:1536
.Lmodx_skip_b0_1:
	s_mul_i32 s0, s38, 2
	s_add_i32 s0, s0, s7
	s_cmp_lt_i32 s0, 0x8800
	s_cbranch_scc0 .Lmodx_skip_b0_2
	s_min_i32 s1, s0, 0x8000
	s_lshr_b32 s1, s1, 12
	s_lshl_b32 s1, s1, 13
	v_add_u32_e32 v5, s1, v3
	s_lshl_b32 s0, s0, 11
	s_add_u32 s2, s64, s0
	s_addc_u32 s3, s65, 0
	ds_read_b128 v[160:163], v5 offset:0
	ds_read_b128 v[164:167], v5 offset:1024
	ds_read_b128 v[168:171], v5 offset:2048
	ds_read_b128 v[172:175], v5 offset:3072
	ds_read_b128 v[176:179], v5 offset:4096
	ds_read_b128 v[180:183], v5 offset:5120
	ds_read_b128 v[184:187], v5 offset:6144
	ds_read_b128 v[188:191], v5 offset:7168
	s_waitcnt lgkmcnt(0)
	v_add_f32_e32 v176, 1.0, v176
	v_add_f32_e32 v177, 1.0, v177
	v_add_f32_e32 v178, 1.0, v178
	v_add_f32_e32 v179, 1.0, v179
	v_fma_f32 v48, v48, v176, v160
	v_fma_f32 v49, v49, v177, v161
	v_fma_f32 v50, v50, v178, v162
	v_fma_f32 v51, v51, v179, v163
	v_cvt_pk_bf16_f32 v192, v48, v49
	v_cvt_pk_bf16_f32 v193, v50, v51
	global_store_dwordx2 v4, v[192:193], s[2:3]
	s_nop 0
	v_add_f32_e32 v180, 1.0, v180
	v_add_f32_e32 v181, 1.0, v181
	v_add_f32_e32 v182, 1.0, v182
	v_add_f32_e32 v183, 1.0, v183
	v_fma_f32 v52, v52, v180, v164
	v_fma_f32 v53, v53, v181, v165
	v_fma_f32 v54, v54, v182, v166
	v_fma_f32 v55, v55, v183, v167
	v_cvt_pk_bf16_f32 v194, v52, v53
	v_cvt_pk_bf16_f32 v195, v54, v55
	global_store_dwordx2 v4, v[194:195], s[2:3] offset:512
	s_nop 0
	v_add_f32_e32 v184, 1.0, v184
	v_add_f32_e32 v185, 1.0, v185
	v_add_f32_e32 v186, 1.0, v186
	v_add_f32_e32 v187, 1.0, v187
	v_fma_f32 v56, v56, v184, v168
	v_fma_f32 v57, v57, v185, v169
	v_fma_f32 v58, v58, v186, v170
	v_fma_f32 v59, v59, v187, v171
	v_cvt_pk_bf16_f32 v196, v56, v57
	v_cvt_pk_bf16_f32 v197, v58, v59
	global_store_dwordx2 v4, v[196:197], s[2:3] offset:1024
	s_nop 0
	v_add_f32_e32 v188, 1.0, v188
	v_add_f32_e32 v189, 1.0, v189
	v_add_f32_e32 v190, 1.0, v190
	v_add_f32_e32 v191, 1.0, v191
	v_fma_f32 v60, v60, v188, v172
	v_fma_f32 v61, v61, v189, v173
	v_fma_f32 v62, v62, v190, v174
	v_fma_f32 v63, v63, v191, v175
	v_cvt_pk_bf16_f32 v198, v60, v61
	v_cvt_pk_bf16_f32 v199, v62, v63
	global_store_dwordx2 v4, v[198:199], s[2:3] offset:1536
; __device__ __forceinline__ unsigned pk2(float lo, float hi) { return f2bf(lo) | (f2bf(hi) << 16); }
; __device__ __forceinline__ void modulate_rows(const Args& a, const float* mod0, bf16* U, int gw, int ngw, int lane) {
;     ...
;         const bool lat = m < ML; const int bb = lat ? (m >> 12) : 8;
;         const float* xr = lat ? a.x + (size_t)m * DM : a.ctx + (size_t)(m - ML) * DM;
;         const float* mp = mod0 + (size_t)bb * 6144;
; #pragma unroll
;         for (int j = 0; j < 4; ++j) { const int col = 4 * (lane + 64 * j); const f32x4 v = *(const f32x4*)(xr + col), sh = *(const f32x4*)(mp + col), sc = *(const f32x4*)(mp + 1024 + col);
;             const f32x4 o = v * (sc + 1.0f) + sh; v2u w; w.x = pk2(o[0], o[1]); w.y = pk2(o[2], o[3]); *(v2u*)(U + (size_t)m * DM + col) = w; }
.Lmodx_skip_b0_2:
	s_mul_i32 s0, s38, 3
	s_add_i32 s0, s0, s7
	s_cmp_lt_i32 s0, 0x8800
	s_cbranch_scc0 .Lmodx_skip_b0_3
	s_min_i32 s1, s0, 0x8000
	s_lshr_b32 s1, s1, 12
	s_lshl_b32 s1, s1, 13
	v_add_u32_e32 v5, s1, v3
	s_lshl_b32 s0, s0, 11
	s_add_u32 s2, s64, s0
	s_addc_u32 s3, s65, 0
	ds_read_b128 v[160:163], v5 offset:0
	ds_read_b128 v[164:167], v5 offset:1024
	ds_read_b128 v[168:171], v5 offset:2048
	ds_read_b128 v[172:175], v5 offset:3072
	ds_read_b128 v[176:179], v5 offset:4096
	ds_read_b128 v[180:183], v5 offset:5120
	ds_read_b128 v[184:187], v5 offset:6144
	ds_read_b128 v[188:191], v5 offset:7168
	s_waitcnt lgkmcnt(0)
	v_add_f32_e32 v176, 1.0, v176
	v_add_f32_e32 v177, 1.0, v177
	v_add_f32_e32 v178, 1.0, v178
	v_add_f32_e32 v179, 1.0, v179
	v_fma_f32 v64, v64, v176, v160
	v_fma_f32 v65, v65, v177, v161
	v_fma_f32 v66, v66, v178, v162
	v_fma_f32 v67, v67, v179, v163
	v_cvt_pk_bf16_f32 v192, v64, v65
	v_cvt_pk_bf16_f32 v193, v66, v67
	global_store_dwordx2 v4, v[192:193], s[2:3]
	s_nop 0
	v_add_f32_e32 v180, 1.0, v180
	v_add_f32_e32 v181, 1.0, v181
	v_add_f32_e32 v182, 1.0, v182
	v_add_f32_e32 v183, 1.0, v183
	v_fma_f32 v68, v68, v180, v164
	v_fma_f32 v69, v69, v181, v165
	v_fma_f32 v70, v70, v182, v166
	v_fma_f32 v71, v71, v183, v167
	v_cvt_pk_bf16_f32 v194, v68, v69
	v_cvt_pk_bf16_f32 v195, v70, v71
	global_store_dwordx2 v4, v[194:195], s[2:3] offset:512
	s_nop 0
	v_add_f32_e32 v184, 1.0, v184
	v_add_f32_e32 v185, 1.0, v185
	v_add_f32_e32 v186, 1.0, v186
	v_add_f32_e32 v187, 1.0, v187
	v_fma_f32 v72, v72, v184, v168
	v_fma_f32 v73, v73, v185, v169
	v_fma_f32 v74, v74, v186, v170
	v_fma_f32 v75, v75, v187, v171
	v_cvt_pk_bf16_f32 v196, v72, v73
	v_cvt_pk_bf16_f32 v197, v74, v75
	global_store_dwordx2 v4, v[196:197], s[2:3] offset:1024
	s_nop 0
	v_add_f32_e32 v188, 1.0, v188
	v_add_f32_e32 v189, 1.0, v189
	v_add_f32_e32 v190, 1.0, v190
	v_add_f32_e32 v191, 1.0, v191
	v_fma_f32 v76, v76, v188, v172
	v_fma_f32 v77, v77, v189, v173
	v_fma_f32 v78, v78, v190, v174
	v_fma_f32 v79, v79, v191, v175
	v_cvt_pk_bf16_f32 v198, v76, v77
	v_cvt_pk_bf16_f32 v199, v78, v79
	global_store_dwordx2 v4, v[198:199], s[2:3] offset:1536
.Lmodx_skip_b0_3:
	s_mov_b32 s7, s11
	s_cmp_lt_i32 s7, 0x8800
	s_cbranch_scc0 .Lmodx_done
	s_lshl_b32 s0, s38, 2
	s_add_i32 s11, s7, s0
	s_mul_i32 s0, s38, 0
	s_add_i32 s0, s0, s11
	s_min_i32 s0, s0, 0x87ff
	s_cmp_lt_i32 s0, 0x8000
	s_cselect_b32 s2, s68, s72
	s_cselect_b32 s3, s69, s73
	s_cselect_b32 s1, 0, 0x8000
	s_sub_i32 s0, s0, s1
	s_lshl_b32 s0, s0, 12
	s_add_u32 s2, s2, s0
	s_addc_u32 s3, s3, 0
	global_load_dwordx4 v[16:19], v3, s[2:3]
	global_load_dwordx4 v[20:23], v3, s[2:3] offset:1024
	global_load_dwordx4 v[24:27], v3, s[2:3] offset:2048
	global_load_dwordx4 v[28:31], v3, s[2:3] offset:3072
	s_mul_i32 s0, s38, 1
	s_add_i32 s0, s0, s11
	s_min_i32 s0, s0, 0x87ff
	s_cmp_lt_i32 s0, 0x8000
	s_cselect_b32 s2, s68, s72
	s_cselect_b32 s3, s69, s73
	s_cselect_b32 s1, 0, 0x8000
	s_sub_i32 s0, s0, s1
	s_lshl_b32 s0, s0, 12
	s_add_u32 s2, s2, s0
	s_addc_u32 s3, s3, 0
	global_load_dwordx4 v[32:35], v3, s[2:3]
	global_load_dwordx4 v[36:39], v3, s[2:3] offset:1024
	global_load_dwordx4 v[40:43], v3, s[2:3] offset:2048
	global_load_dwordx4 v[44:47], v3, s[2:3] offset:3072
	s_mul_i32 s0, s38, 2
	s_add_i32 s0, s0, s11
	s_min_i32 s0, s0, 0x87ff
	s_cmp_lt_i32 s0, 0x8000
	s_cselect_b32 s2, s68, s72
	s_cselect_b32 s3, s69, s73
	s_cselect_b32 s1, 0, 0x8000
	s_sub_i32 s0, s0, s1
	s_lshl_b32 s0, s0, 12
	s_add_u32 s2, s2, s0
	s_addc_u32 s3, s3, 0
	global_load_dwordx4 v[48:51], v3, s[2:3]
	global_load_dwordx4 v[52:55], v3, s[2:3] offset:1024
	global_load_dwordx4 v[56:59], v3, s[2:3] offset:2048
	global_load_dwordx4 v[60:63], v3, s[2:3] offset:3072
	s_mul_i32 s0, s38, 3
	s_add_i32 s0, s0, s11
	s_min_i32 s0, s0, 0x87ff
	s_cmp_lt_i32 s0, 0x8000
	s_cselect_b32 s2, s68, s72
	s_cselect_b32 s3, s69, s73
	s_cselect_b32 s1, 0, 0x8000
	s_sub_i32 s0, s0, s1
	s_lshl_b32 s0, s0, 12
	s_add_u32 s2, s2, s0
	s_addc_u32 s3, s3, 0
	global_load_dwordx4 v[64:67], v3, s[2:3]
	global_load_dwordx4 v[68:71], v3, s[2:3] offset:1024
	global_load_dwordx4 v[72:75], v3, s[2:3] offset:2048
	global_load_dwordx4 v[76:79], v3, s[2:3] offset:3072
	s_waitcnt vmcnt(32)
	s_mul_i32 s0, s38, 0
	s_add_i32 s0, s0, s7
	s_cmp_lt_i32 s0, 0x8800
	s_cbranch_scc0 .Lmodx_skip_b1_0
	s_min_i32 s1, s0, 0x8000
	s_lshr_b32 s1, s1, 12
	s_lshl_b32 s1, s1, 13
	v_add_u32_e32 v5, s1, v3
	s_lshl_b32 s0, s0, 11
	s_add_u32 s2, s64, s0
	s_addc_u32 s3, s65, 0
	ds_read_b128 v[160:163], v5 offset:0
	ds_read_b128 v[164:167], v5 offset:1024
	ds_read_b128 v[168:171], v5 offset:2048
	ds_read_b128 v[172:175], v5 offset:3072
	ds_read_b128 v[176:179], v5 offset:4096
	ds_read_b128 v[180:183], v5 offset:5120
	ds_read_b128 v[184:187], v5 offset:6144
	ds_read_b128 v[188:191], v5 offset:7168
	s_waitcnt lgkmcnt(0)
	v_add_f32_e32 v176, 1.0, v176
	v_add_f32_e32 v177, 1.0, v177
	v_add_f32_e32 v178, 1.0, v178
	v_add_f32_e32 v179, 1.0, v179
	v_fma_f32 v96, v96, v176, v160
	v_fma_f32 v97, v97, v177, v161
	v_fma_f32 v98, v98, v178, v162
	v_fma_f32 v99, v99, v179, v163
	v_cvt_pk_bf16_f32 v192, v96, v97
	v_cvt_pk_bf16_f32 v193, v98, v99
	global_store_dwordx2 v4, v[192:193], s[2:3]
	s_nop 0
	v_add_f32_e32 v180, 1.0, v180
	v_add_f32_e32 v181, 1.0, v181
	v_add_f32_e32 v182, 1.0, v182
	v_add_f32_e32 v183, 1.0, v183
	v_fma_f32 v100, v100, v180, v164
	v_fma_f32 v101, v101, v181, v165
	v_fma_f32 v102, v102, v182, v166
	v_fma_f32 v103, v103, v183, v167
	v_cvt_pk_bf16_f32 v194, v100, v101
	v_cvt_pk_bf16_f32 v195, v102, v103
	global_store_dwordx2 v4, v[194:195], s[2:3] offset:512
	s_nop 0
	v_add_f32_e32 v184, 1.0, v184
	v_add_f32_e32 v185, 1.0, v185
	v_add_f32_e32 v186, 1.0, v186
	v_add_f32_e32 v187, 1.0, v187
	v_fma_f32 v104, v104, v184, v168
	v_fma_f32 v105, v105, v185, v169
	v_fma_f32 v106, v106, v186, v170
	v_fma_f32 v107, v107, v187, v171
	v_cvt_pk_bf16_f32 v196, v104, v105
	v_cvt_pk_bf16_f32 v197, v106, v107
	global_store_dwordx2 v4, v[196:197], s[2:3] offset:1024
	s_nop 0
	v_add_f32_e32 v188, 1.0, v188
	v_add_f32_e32 v189, 1.0, v189
	v_add_f32_e32 v190, 1.0, v190
	v_add_f32_e32 v191, 1.0, v191
	v_fma_f32 v108, v108, v188, v172
	v_fma_f32 v109, v109, v189, v173
	v_fma_f32 v110, v110, v190, v174
	v_fma_f32 v111, v111, v191, v175
	v_cvt_pk_bf16_f32 v198, v108, v109
	v_cvt_pk_bf16_f32 v199, v110, v111
	global_store_dwordx2 v4, v[198:199], s[2:3] offset:1536
; __device__ __forceinline__ unsigned pk2(float lo, float hi) { return f2bf(lo) | (f2bf(hi) << 16); }
; __device__ __forceinline__ void modulate_rows(const Args& a, const float* mod0, bf16* U, int gw, int ngw, int lane) {
;     ...
;         const bool lat = m < ML; const int bb = lat ? (m >> 12) : 8;
;         const float* xr = lat ? a.x + (size_t)m * DM : a.ctx + (size_t)(m - ML) * DM;
;         const float* mp = mod0 + (size_t)bb * 6144;
; #pragma unroll
;         for (int j = 0; j < 4; ++j) { const int col = 4 * (lane + 64 * j); const f32x4 v = *(const f32x4*)(xr + col), sh = *(const f32x4*)(mp + col), sc = *(const f32x4*)(mp + 1024 + col);
;             const f32x4 o = v * (sc + 1.0f) + sh; v2u w; w.x = pk2(o[0], o[1]); w.y = pk2(o[2], o[3]); *(v2u*)(U + (size_t)m * DM + col) = w; }
.Lmodx_skip_b1_0:
	s_mul_i32 s0, s38, 1
	s_add_i32 s0, s0, s7
	s_cmp_lt_i32 s0, 0x8800
	s_cbranch_scc0 .Lmodx_skip_b1_1
	s_min_i32 s1, s0, 0x8000
	s_lshr_b32 s1, s1, 12
	s_lshl_b32 s1, s1, 13
	v_add_u32_e32 v5, s1, v3
	s_lshl_b32 s0, s0, 11
	s_add_u32 s2, s64, s0
	s_addc_u32 s3, s65, 0
	ds_read_b128 v[160:163], v5 offset:0
	ds_read_b128 v[164:167], v5 offset:1024
	ds_read_b128 v[168:171], v5 offset:2048
	ds_read_b128 v[172:175], v5 offset:3072
	ds_read_b128 v[176:179], v5 offset:4096
	ds_read_b128 v[180:183], v5 offset:5120
	ds_read_b128 v[184:187], v5 offset:6144
	ds_read_b128 v[188:191], v5 offset:7168
	s_waitcnt lgkmcnt(0)
	v_add_f32_e32 v176, 1.0, v176
	v_add_f32_e32 v177, 1.0, v177
	v_add_f32_e32 v178, 1.0, v178
	v_add_f32_e32 v179, 1.0, v179
	v_fma_f32 v112, v112, v176, v160
	v_fma_f32 v113, v113, v177, v161
	v_fma_f32 v114, v114, v178, v162
	v_fma_f32 v115, v115, v179, v163
	v_cvt_pk_bf16_f32 v192, v112, v113
	v_cvt_pk_bf16_f32 v193, v114, v115
	global_store_dwordx2 v4, v[192:193], s[2:3]
	s_nop 0
	v_add_f32_e32 v180, 1.0, v180
	v_add_f32_e32 v181, 1.0, v181
	v_add_f32_e32 v182, 1.0, v182
	v_add_f32_e32 v183, 1.0, v183
	v_fma_f32 v116, v116, v180, v164
	v_fma_f32 v117, v117, v181, v165
	v_fma_f32 v118, v118, v182, v166
	v_fma_f32 v119, v119, v183, v167
	v_cvt_pk_bf16_f32 v194, v116, v117
	v_cvt_pk_bf16_f32 v195, v118, v119
	global_store_dwordx2 v4, v[194:195], s[2:3] offset:512
	s_nop 0
	v_add_f32_e32 v184, 1.0, v184
	v_add_f32_e32 v185, 1.0, v185
	v_add_f32_e32 v186, 1.0, v186
	v_add_f32_e32 v187, 1.0, v187
	v_fma_f32 v120, v120, v184, v168
	v_fma_f32 v121, v121, v185, v169
	v_fma_f32 v122, v122, v186, v170
	v_fma_f32 v123, v123, v187, v171
	v_cvt_pk_bf16_f32 v196, v120, v121
	v_cvt_pk_bf16_f32 v197, v122, v123
	global_store_dwordx2 v4, v[196:197], s[2:3] offset:1024
	s_nop 0
	v_add_f32_e32 v188, 1.0, v188
	v_add_f32_e32 v189, 1.0, v189
	v_add_f32_e32 v190, 1.0, v190
	v_add_f32_e32 v191, 1.0, v191
	v_fma_f32 v124, v124, v188, v172
	v_fma_f32 v125, v125, v189, v173
	v_fma_f32 v126, v126, v190, v174
	v_fma_f32 v127, v127, v191, v175
	v_cvt_pk_bf16_f32 v198, v124, v125
	v_cvt_pk_bf16_f32 v199, v126, v127
	global_store_dwordx2 v4, v[198:199], s[2:3] offset:1536
.Lmodx_skip_b1_1:
	s_mul_i32 s0, s38, 2
	s_add_i32 s0, s0, s7
	s_cmp_lt_i32 s0, 0x8800
	s_cbranch_scc0 .Lmodx_skip_b1_2
	s_min_i32 s1, s0, 0x8000
	s_lshr_b32 s1, s1, 12
	s_lshl_b32 s1, s1, 13
	v_add_u32_e32 v5, s1, v3
	s_lshl_b32 s0, s0, 11
	s_add_u32 s2, s64, s0
	s_addc_u32 s3, s65, 0
	ds_read_b128 v[160:163], v5 offset:0
	ds_read_b128 v[164:167], v5 offset:1024
	ds_read_b128 v[168:171], v5 offset:2048
	ds_read_b128 v[172:175], v5 offset:3072
	ds_read_b128 v[176:179], v5 offset:4096
	ds_read_b128 v[180:183], v5 offset:5120
	ds_read_b128 v[184:187], v5 offset:6144
	ds_read_b128 v[188:191], v5 offset:7168
	s_waitcnt lgkmcnt(0)
	v_add_f32_e32 v176, 1.0, v176
	v_add_f32_e32 v177, 1.0, v177
	v_add_f32_e32 v178, 1.0, v178
	v_add_f32_e32 v179, 1.0, v179
	v_fma_f32 v128, v128, v176, v160
	v_fma_f32 v129, v129, v177, v161
	v_fma_f32 v130, v130, v178, v162
	v_fma_f32 v131, v131, v179, v163
	v_cvt_pk_bf16_f32 v192, v128, v129
	v_cvt_pk_bf16_f32 v193, v130, v131
	global_store_dwordx2 v4, v[192:193], s[2:3]
	s_nop 0
	v_add_f32_e32 v180, 1.0, v180
	v_add_f32_e32 v181, 1.0, v181
	v_add_f32_e32 v182, 1.0, v182
	v_add_f32_e32 v183, 1.0, v183
	v_fma_f32 v132, v132, v180, v164
	v_fma_f32 v133, v133, v181, v165
	v_fma_f32 v134, v134, v182, v166
	v_fma_f32 v135, v135, v183, v167
	v_cvt_pk_bf16_f32 v194, v132, v133
	v_cvt_pk_bf16_f32 v195, v134, v135
	global_store_dwordx2 v4, v[194:195], s[2:3] offset:512
	s_nop 0
	v_add_f32_e32 v184, 1.0, v184
	v_add_f32_e32 v185, 1.0, v185
	v_add_f32_e32 v186, 1.0, v186
	v_add_f32_e32 v187, 1.0, v187
	v_fma_f32 v136, v136, v184, v168
	v_fma_f32 v137, v137, v185, v169
	v_fma_f32 v138, v138, v186, v170
	v_fma_f32 v139, v139, v187, v171
	v_cvt_pk_bf16_f32 v196, v136, v137
	v_cvt_pk_bf16_f32 v197, v138, v139
	global_store_dwordx2 v4, v[196:197], s[2:3] offset:1024
	s_nop 0
	v_add_f32_e32 v188, 1.0, v188
	v_add_f32_e32 v189, 1.0, v189
	v_add_f32_e32 v190, 1.0, v190
	v_add_f32_e32 v191, 1.0, v191
	v_fma_f32 v140, v140, v188, v172
	v_fma_f32 v141, v141, v189, v173
	v_fma_f32 v142, v142, v190, v174
	v_fma_f32 v143, v143, v191, v175
	v_cvt_pk_bf16_f32 v198, v140, v141
	v_cvt_pk_bf16_f32 v199, v142, v143
	global_store_dwordx2 v4, v[198:199], s[2:3] offset:1536
; __device__ __forceinline__ unsigned pk2(float lo, float hi) { return f2bf(lo) | (f2bf(hi) << 16); }
; __device__ __forceinline__ unsigned xb_ld(unsigned* p)              { return __hip_atomic_load(p, __ATOMIC_RELAXED, __HIP_MEMORY_SCOPE_AGENT); }
; __device__ __forceinline__ void xcd_barrier_complete(unsigned* bar, unsigned x, unsigned& nloc, unsigned& nx) {
;     const unsigned G = gridDim.x * gridDim.y * gridDim.z;
;     unsigned sum, cnt, mine, sp = 0u;
;     for (;;) {
;         sum = 0u; cnt = 0u; mine = 0u;
; #pragma unroll
;         for (unsigned j = 0; j < 16; ++j) { const unsigned c = xb_ld(&bar[XB_XCNT(j)]); sum += c; cnt += (c > 0u) ? 1u : 0u; mine = (j == x) ? c : mine; }
;         if (sum == G) break;
;         __builtin_amdgcn_s_sleep(1);
;         if ((++sp & 255u) == 0u) { if (xb_ld(&bar[XB_TMO])) break; if (sp > XB_SPIN_CAP) { atomicAdd(&bar[XB_TMO], 1u); break; } }
;     }
;     nloc = mine > 0u ? mine : 1u; nx = cnt > 0u ? cnt : 1u;
; }
; __device__ __forceinline__ void xcd_barrier(const XcdBarrier& b) {
;     asm volatile("s_waitcnt vmcnt(0)" ::: "memory");
;     __syncthreads();
;     if (threadIdx.x == 0) {
;         unsigned* bar = b.bar;
;         __builtin_amdgcn_s_waitcnt(0);
;         unsigned nloc = b.st[0], nx = b.st[1];
;         if (nloc == 0u) { xcd_barrier_complete(bar, b.x, nloc, nx); b.st[0] = nloc; b.st[1] = nx; }
; __device__ __forceinline__ void modulate_rows(const Args& a, const float* mod0, bf16* U, int gw, int ngw, int lane) {
;     ...
;         const bool lat = m < ML; const int bb = lat ? (m >> 12) : 8;
;         const float* xr = lat ? a.x + (size_t)m * DM : a.ctx + (size_t)(m - ML) * DM;
;         const float* mp = mod0 + (size_t)bb * 6144;
; #pragma unroll
;         for (int j = 0; j < 4; ++j) { const int col = 4 * (lane + 64 * j); const f32x4 v = *(const f32x4*)(xr + col), sh = *(const f32x4*)(mp + col), sc = *(const f32x4*)(mp + 1024 + col);
;             const f32x4 o = v * (sc + 1.0f) + sh; v2u w; w.x = pk2(o[0], o[1]); w.y = pk2(o[2], o[3]); *(v2u*)(U + (size_t)m * DM + col) = w; }
.Lmodx_skip_b1_2:
	s_mul_i32 s0, s38, 3
	s_add_i32 s0, s0, s7
	s_cmp_lt_i32 s0, 0x8800
	s_cbranch_scc0 .Lmodx_skip_b1_3
	s_min_i32 s1, s0, 0x8000
	s_lshr_b32 s1, s1, 12
	s_lshl_b32 s1, s1, 13
	v_add_u32_e32 v5, s1, v3
	s_lshl_b32 s0, s0, 11
	s_add_u32 s2, s64, s0
	s_addc_u32 s3, s65, 0
	ds_read_b128 v[160:163], v5 offset:0
	ds_read_b128 v[164:167], v5 offset:1024
	ds_read_b128 v[168:171], v5 offset:2048
	ds_read_b128 v[172:175], v5 offset:3072
	ds_read_b128 v[176:179], v5 offset:4096
	ds_read_b128 v[180:183], v5 offset:5120
	ds_read_b128 v[184:187], v5 offset:6144
	ds_read_b128 v[188:191], v5 offset:7168
	s_waitcnt lgkmcnt(0)
	v_add_f32_e32 v176, 1.0, v176
	v_add_f32_e32 v177, 1.0, v177
	v_add_f32_e32 v178, 1.0, v178
	v_add_f32_e32 v179, 1.0, v179
	v_fma_f32 v144, v144, v176, v160
	v_fma_f32 v145, v145, v177, v161
	v_fma_f32 v146, v146, v178, v162
	v_fma_f32 v147, v147, v179, v163
	v_cvt_pk_bf16_f32 v192, v144, v145
	v_cvt_pk_bf16_f32 v193, v146, v147
	global_store_dwordx2 v4, v[192:193], s[2:3]
	s_nop 0
	v_add_f32_e32 v180, 1.0, v180
	v_add_f32_e32 v181, 1.0, v181
	v_add_f32_e32 v182, 1.0, v182
	v_add_f32_e32 v183, 1.0, v183
	v_fma_f32 v148, v148, v180, v164
	v_fma_f32 v149, v149, v181, v165
	v_fma_f32 v150, v150, v182, v166
	v_fma_f32 v151, v151, v183, v167
	v_cvt_pk_bf16_f32 v194, v148, v149
	v_cvt_pk_bf16_f32 v195, v150, v151
	global_store_dwordx2 v4, v[194:195], s[2:3] offset:512
	s_nop 0
	v_add_f32_e32 v184, 1.0, v184
	v_add_f32_e32 v185, 1.0, v185
	v_add_f32_e32 v186, 1.0, v186
	v_add_f32_e32 v187, 1.0, v187
	v_fma_f32 v152, v152, v184, v168
	v_fma_f32 v153, v153, v185, v169
	v_fma_f32 v154, v154, v186, v170
	v_fma_f32 v155, v155, v187, v171
	v_cvt_pk_bf16_f32 v196, v152, v153
	v_cvt_pk_bf16_f32 v197, v154, v155
	global_store_dwordx2 v4, v[196:197], s[2:3] offset:1024
	s_nop 0
	v_add_f32_e32 v188, 1.0, v188
	v_add_f32_e32 v189, 1.0, v189
	v_add_f32_e32 v190, 1.0, v190
	v_add_f32_e32 v191, 1.0, v191
	v_fma_f32 v156, v156, v188, v172
	v_fma_f32 v157, v157, v189, v173
	v_fma_f32 v158, v158, v190, v174
	v_fma_f32 v159, v159, v191, v175
	v_cvt_pk_bf16_f32 v198, v156, v157
	v_cvt_pk_bf16_f32 v199, v158, v159
	global_store_dwordx2 v4, v[198:199], s[2:3] offset:1536
.Lmodx_skip_b1_3:
	s_mov_b32 s7, s11
	s_cmp_lt_i32 s7, 0x8800
	s_cbranch_scc0 .Lmodx_done
	s_branch .Lmodx_loop
.Lmodx_done:
	s_waitcnt vmcnt(0)
.LBB0_84:
	s_getreg_b32 s2, hwreg(HW_REG_XCC_ID, 0, 4)
	s_waitcnt vmcnt(0)
	v_readlane_b32 s4, v252, 0
	v_readlane_b32 s5, v252, 1
	s_barrier
	s_and_saveexec_b64 s[0:1], s[4:5]
	s_cbranch_execz .LBB0_136
	s_add_i32 s3, 0, 0x25fc0
	v_mov_b32_e32 v0, s3
	s_waitcnt vmcnt(0) expcnt(0) lgkmcnt(0)
	ds_read_b32 v2, v0
	s_add_i32 s3, 0, 0x25fc4
	v_mov_b32_e32 v0, s3
	ds_read_b32 v0, v0
	s_mov_b32 s4, s38
	s_waitcnt lgkmcnt(1)
	v_cmp_ne_u32_e32 vcc, 0, v2
	s_and_b32 s46, s2, 15
	s_cbranch_vccnz .LBB0_100
	s_add_u32 s2, s94, 0x1ef00200
	s_addc_u32 s3, s95, 0
	s_add_u32 s6, s94, 0x1ef00400
	s_addc_u32 s7, s95, 0
	s_add_u32 s8, s94, 0x1ef00500
	s_addc_u32 s9, s95, 0
	s_add_u32 s10, s94, 0x1ef00600
	s_addc_u32 s11, s95, 0
	s_add_u32 s12, s94, 0x1ef00700
	s_addc_u32 s13, s95, 0
	s_add_u32 s14, s94, 0x1ef00800
	s_addc_u32 s15, s95, 0
	s_add_u32 s16, s94, 0x1ef00900
	s_addc_u32 s17, s95, 0
	s_add_u32 s18, s94, 0x1ef00a00
	s_addc_u32 s19, s95, 0
	s_add_u32 s20, s94, 0x1ef00b00
	s_addc_u32 s21, s95, 0
	s_add_u32 s22, s94, 0x1ef00c00
	s_addc_u32 s23, s95, 0
	s_add_u32 s24, s94, 0x1ef00d00
	s_addc_u32 s25, s95, 0
	s_add_u32 s26, s94, 0x1ef00e00
	s_addc_u32 s27, s95, 0
	s_add_u32 s28, s94, 0x1ef00f00
	s_addc_u32 s29, s95, 0
	s_add_u32 s30, s94, 0x1ef01000
	s_addc_u32 s31, s95, 0
	s_add_u32 s34, s94, 0x1ef01100
	s_addc_u32 s35, s95, 0
	s_add_u32 s36, s94, 0x1ef01200
	s_addc_u32 s37, s95, 0
	s_mul_i32 s47, s61, s33
	s_add_u32 s38, s94, 0x1ef01300
	s_mul_i32 s47, s47, s60
	s_addc_u32 s39, s95, 0
	s_mov_b32 s48, 1
	v_mov_b32_e32 v16, 0
	s_branch .LBB0_88
